# v10 + fragment address math hoisted out of the tile loop (tile start is now just 4 adds + the K reads)
# speedup vs baseline: 1.0061x; 1.0014x over previous
.LBB0_531:
	s_add_i32 s10, s33, 2
	s_cmp_ge_u32 s10, s28
	s_cselect_b64 s[22:23], -1, 0
	s_mov_b64 s[34:35], -1
	s_cmp_gt_i32 s33, s21
	s_cbranch_scc1 .Lat1_skip
	s_and_b64 vcc, exec, s[22:23]
	s_cbranch_vccnz .Lat1_nodma
	s_setprio 3
	s_mul_i32 s10, s0, 0xa000
	v_add_u32_e32 v14, s10, v0
	v_add_u32_e32 v15, s10, v212
	v_add_u32_e32 v176, s10, v213
	v_add_u32_e32 v177, s10, v219
	ds_read_b128 v[144:147], v14 offset:0
	ds_read_b128 v[148:151], v15 offset:0
	ds_read_b128 v[152:155], v176 offset:0
	ds_read_b128 v[156:159], v177 offset:0
	ds_read_b128 v[160:163], v14 offset:8192
	ds_read_b128 v[164:167], v15 offset:8192
	ds_read_b128 v[168:171], v176 offset:8192
	ds_read_b128 v[172:175], v177 offset:8192
	ds_read_b128 v[2:5], v14 offset:16384
	ds_read_b128 v[6:9], v15 offset:16384
	ds_read_b128 v[10:13], v176 offset:16384
	ds_read_b128 v[238:241], v177 offset:16384
	s_waitcnt lgkmcnt(8)
	v_mfma_f32_32x32x16_bf16 v[80:95], v[144:147], v[132:135], 0
	v_mfma_f32_32x32x16_bf16 v[80:95], v[148:151], v[128:131], v[80:95]
	v_mfma_f32_32x32x16_bf16 v[80:95], v[152:155], v[124:127], v[80:95]
	v_mfma_f32_32x32x16_bf16 v[80:95], v[156:159], v[120:123], v[80:95]
	ds_read_b128 v[144:147], v14 offset:4096
	ds_read_b128 v[148:151], v15 offset:4096
	ds_read_b128 v[152:155], v176 offset:4096
	ds_read_b128 v[156:159], v177 offset:4096
	s_waitcnt lgkmcnt(8)
	v_mfma_f32_32x32x16_bf16 v[80:95], v[160:163], v[116:119], v[80:95]
	v_mfma_f32_32x32x16_bf16 v[80:95], v[164:167], v[112:115], v[80:95]
	v_mfma_f32_32x32x16_bf16 v[80:95], v[168:171], v[108:111], v[80:95]
	v_mfma_f32_32x32x16_bf16 v[80:95], v[172:175], v[104:107], v[80:95]
	ds_read_b128 v[160:163], v14 offset:12288
	ds_read_b128 v[164:167], v15 offset:12288
	ds_read_b128 v[168:171], v176 offset:12288
	ds_read_b128 v[172:175], v177 offset:12288
	s_waitcnt lgkmcnt(8)
	v_mfma_f32_32x32x16_bf16 v[80:95], v[2:5], v[100:103], v[80:95]
	v_mfma_f32_32x32x16_bf16 v[80:95], v[6:9], v[140:143], v[80:95]
	v_mfma_f32_32x32x16_bf16 v[80:95], v[10:13], v[96:99], v[80:95]
	v_mfma_f32_32x32x16_bf16 v[80:95], v[238:241], v[136:139], v[80:95]
	s_setprio 2
	ds_read_b128 v[2:5], v14 offset:20480
	ds_read_b128 v[6:9], v15 offset:20480
	ds_read_b128 v[10:13], v176 offset:20480
	ds_read_b128 v[238:241], v177 offset:20480
	s_waitcnt lgkmcnt(8)
	v_mfma_f32_32x32x16_bf16 v[184:199], v[144:147], v[132:135], 0
	v_mfma_f32_32x32x16_bf16 v[184:199], v[148:151], v[128:131], v[184:199]
	v_mfma_f32_32x32x16_bf16 v[184:199], v[152:155], v[124:127], v[184:199]
	v_mfma_f32_32x32x16_bf16 v[184:199], v[156:159], v[120:123], v[184:199]
	ds_read_b128 v[144:147], v14 offset:24576
	ds_read_b128 v[148:151], v14 offset:28672
	ds_read_b128 v[152:155], v14 offset:32768
	ds_read_b128 v[156:159], v14 offset:36864
	s_waitcnt lgkmcnt(8)
	v_mfma_f32_32x32x16_bf16 v[184:199], v[160:163], v[116:119], v[184:199]
	v_med3_f32 v80, v80, s4, v236
	v_exp_f32_e32 v80, v80
	v_med3_f32 v81, v81, s4, v236
	v_exp_f32_e32 v81, v81
	v_mfma_f32_32x32x16_bf16 v[184:199], v[164:167], v[112:115], v[184:199]
	v_med3_f32 v82, v82, s4, v236
	v_exp_f32_e32 v82, v82
	v_med3_f32 v83, v83, s4, v236
	v_exp_f32_e32 v83, v83
	v_mfma_f32_32x32x16_bf16 v[184:199], v[168:171], v[108:111], v[184:199]
	v_med3_f32 v84, v84, s4, v236
	v_exp_f32_e32 v84, v84
	v_med3_f32 v85, v85, s4, v236
	v_exp_f32_e32 v85, v85
	v_mfma_f32_32x32x16_bf16 v[184:199], v[172:175], v[104:107], v[184:199]
	v_med3_f32 v86, v86, s4, v236
	v_exp_f32_e32 v86, v86
	v_med3_f32 v87, v87, s4, v236
	v_exp_f32_e32 v87, v87
	ds_read_b128 v[160:163], v15 offset:24576
	ds_read_b128 v[164:167], v15 offset:28672
	ds_read_b128 v[168:171], v15 offset:32768
	ds_read_b128 v[172:175], v15 offset:36864
	s_waitcnt lgkmcnt(8)
	v_mfma_f32_32x32x16_bf16 v[184:199], v[2:5], v[100:103], v[184:199]
	v_med3_f32 v88, v88, s4, v236
	v_exp_f32_e32 v88, v88
	v_med3_f32 v89, v89, s4, v236
	v_exp_f32_e32 v89, v89
	v_add_f32_e32 v200, v80, v81
	v_add_f32_e32 v200, v200, v82
	v_mfma_f32_32x32x16_bf16 v[184:199], v[6:9], v[140:143], v[184:199]
	v_med3_f32 v90, v90, s4, v236
	v_exp_f32_e32 v90, v90
	v_med3_f32 v91, v91, s4, v236
	v_exp_f32_e32 v91, v91
	v_add_f32_e32 v200, v200, v83
	v_add_f32_e32 v200, v200, v84
	v_mfma_f32_32x32x16_bf16 v[184:199], v[10:13], v[96:99], v[184:199]
	v_med3_f32 v92, v92, s4, v236
	v_exp_f32_e32 v92, v92
	v_med3_f32 v93, v93, s4, v236
	v_exp_f32_e32 v93, v93
	v_add_f32_e32 v200, v200, v85
	v_add_f32_e32 v200, v200, v86
	v_mfma_f32_32x32x16_bf16 v[184:199], v[238:241], v[136:139], v[184:199]
	v_med3_f32 v94, v94, s4, v236
	v_exp_f32_e32 v94, v94
	v_med3_f32 v95, v95, s4, v236
	v_exp_f32_e32 v95, v95
	v_add_f32_e32 v200, v200, v87
	s_setprio 1
	ds_read_b128 v[2:5], v176 offset:24576
	ds_read_b128 v[6:9], v176 offset:28672
	ds_read_b128 v[10:13], v176 offset:32768
	ds_read_b128 v[238:241], v176 offset:36864
	v_cvt_pk_bf16_f32 v80, v80, v81
	v_cvt_pk_bf16_f32 v81, v82, v83
	v_cvt_pk_bf16_f32 v82, v84, v85
	v_cvt_pk_bf16_f32 v83, v86, v87
	v_add_f32_e32 v200, v200, v88
	v_add_f32_e32 v200, v200, v89
	s_waitcnt lgkmcnt(8)
	v_mfma_f32_32x32x16_bf16 v[64:79], v[80:83], v[144:147], v[64:79]
	v_med3_f32 v184, v184, s4, v236
	v_exp_f32_e32 v184, v184
	v_med3_f32 v185, v185, s4, v236
	v_exp_f32_e32 v185, v185
	v_add_f32_e32 v200, v200, v90
	v_add_f32_e32 v200, v200, v91
	v_mfma_f32_32x32x16_bf16 v[48:63], v[80:83], v[148:151], v[48:63]
	v_med3_f32 v186, v186, s4, v236
	v_exp_f32_e32 v186, v186
	v_med3_f32 v187, v187, s4, v236
	v_exp_f32_e32 v187, v187
	v_add_f32_e32 v200, v200, v92
	v_add_f32_e32 v200, v200, v93
	v_mfma_f32_32x32x16_bf16 v[32:47], v[80:83], v[152:155], v[32:47]
	v_med3_f32 v188, v188, s4, v236
	v_exp_f32_e32 v188, v188
	v_med3_f32 v189, v189, s4, v236
	v_exp_f32_e32 v189, v189
	v_add_f32_e32 v200, v200, v94
	v_add_f32_e32 v200, v200, v95
	v_mfma_f32_32x32x16_bf16 v[16:31], v[80:83], v[156:159], v[16:31]
	v_med3_f32 v190, v190, s4, v236
	v_exp_f32_e32 v190, v190
	v_med3_f32 v191, v191, s4, v236
	v_exp_f32_e32 v191, v191
	v_cvt_pk_bf16_f32 v84, v88, v89
	v_cvt_pk_bf16_f32 v85, v90, v91
	v_cvt_pk_bf16_f32 v86, v92, v93
	v_cvt_pk_bf16_f32 v87, v94, v95
	ds_read_b128 v[144:147], v177 offset:24576
	ds_read_b128 v[148:151], v177 offset:28672
	ds_read_b128 v[152:155], v177 offset:32768
	ds_read_b128 v[156:159], v177 offset:36864
	s_waitcnt lgkmcnt(8)
	v_mfma_f32_32x32x16_bf16 v[64:79], v[84:87], v[160:163], v[64:79]
	v_med3_f32 v192, v192, s4, v236
	v_exp_f32_e32 v192, v192
	v_med3_f32 v193, v193, s4, v236
	v_exp_f32_e32 v193, v193
	v_add_f32_e32 v201, v184, v185
	v_add_f32_e32 v201, v201, v186
	v_mfma_f32_32x32x16_bf16 v[48:63], v[84:87], v[164:167], v[48:63]
	v_med3_f32 v194, v194, s4, v236
	v_exp_f32_e32 v194, v194
	v_med3_f32 v195, v195, s4, v236
	v_exp_f32_e32 v195, v195
	v_add_f32_e32 v201, v201, v187
	v_add_f32_e32 v201, v201, v188
	v_mfma_f32_32x32x16_bf16 v[32:47], v[84:87], v[168:171], v[32:47]
	v_med3_f32 v196, v196, s4, v236
	v_exp_f32_e32 v196, v196
	v_med3_f32 v197, v197, s4, v236
	v_exp_f32_e32 v197, v197
	v_add_f32_e32 v201, v201, v189
	v_mfma_f32_32x32x16_bf16 v[16:31], v[84:87], v[172:175], v[16:31]
	v_med3_f32 v198, v198, s4, v236
	v_exp_f32_e32 v198, v198
	v_med3_f32 v199, v199, s4, v236
	v_exp_f32_e32 v199, v199
	v_add_f32_e32 v201, v201, v190
	v_cvt_pk_bf16_f32 v184, v184, v185
	v_cvt_pk_bf16_f32 v185, v186, v187
	v_cvt_pk_bf16_f32 v186, v188, v189
	v_cvt_pk_bf16_f32 v187, v190, v191
	v_add_f32_e32 v201, v201, v191
	s_setprio 0
	s_waitcnt lgkmcnt(4)
	v_mfma_f32_32x32x16_bf16 v[64:79], v[184:187], v[2:5], v[64:79]
	v_mad_u64_u32 v[202:203], s[10:11], s86, v228, v[180:181]
	s_mul_i32 s10, s7, 0xa000
	s_add_i32 s10, s9, s10
	s_mov_b32 m0, s10
	v_lshl_add_u64 v[204:205], v[202:203], 0, s[94:95]
	global_load_lds_dwordx4 v[202:203], off
	v_add_f32_e32 v201, v201, v192
	v_add_f32_e32 v201, v201, v193
	v_add_f32_e32 v201, v201, v194
	v_mfma_f32_32x32x16_bf16 v[48:63], v[184:187], v[6:9], v[48:63]
	s_add_i32 m0, s10, 0x2000
	v_lshl_add_u64 v[202:203], v[202:203], 0, s[96:97]
	global_load_lds_dwordx4 v[204:205], off
	v_add_f32_e32 v201, v201, v195
	v_add_f32_e32 v201, v201, v196
	v_add_f32_e32 v201, v201, v197
	v_mfma_f32_32x32x16_bf16 v[32:47], v[184:187], v[10:13], v[32:47]
	s_add_i32 m0, s10, 0x4000
	s_nop 0
	global_load_lds_dwordx4 v[202:203], off
	v_lshl_add_u64 v[202:203], s[86:87], 1, v[182:183]
	s_add_i32 m0, s10, 0x6000
	v_add_f32_e32 v201, v201, v198
	v_add_f32_e32 v201, v201, v199
	v_cvt_pk_bf16_f32 v188, v192, v193
	v_cvt_pk_bf16_f32 v189, v194, v195
	v_cvt_pk_bf16_f32 v190, v196, v197
	v_cvt_pk_bf16_f32 v191, v198, v199
	v_mfma_f32_32x32x16_bf16 v[16:31], v[184:187], v[238:241], v[16:31]
	global_load_lds_dwordx4 v[202:203], off
	v_lshl_add_u64 v[202:203], v[202:203], 0, s[92:93]
	s_add_i32 m0, s10, 0x8000
	v_add_f32_e32 v200, v200, v201
	v_add_f32_e32 v218, v218, v200
	s_waitcnt lgkmcnt(0)
	v_mfma_f32_32x32x16_bf16 v[64:79], v[188:191], v[144:147], v[64:79]
	global_load_lds_dwordx4 v[202:203], off
	v_mfma_f32_32x32x16_bf16 v[48:63], v[188:191], v[148:151], v[48:63]
	v_mfma_f32_32x32x16_bf16 v[32:47], v[188:191], v[152:155], v[32:47]
	v_mfma_f32_32x32x16_bf16 v[16:31], v[188:191], v[156:159], v[16:31]
	s_waitcnt vmcnt(5) lgkmcnt(0)
	s_branch .LBB0_530

.LBB0_574:
	s_add_i32 s10, s33, 2
	s_cmp_ge_i32 s10, s21
	s_cselect_b64 s[22:23], -1, 0
	s_mov_b64 s[34:35], -1
	s_cmp_gt_i32 s33, s9
	s_cbranch_scc1 .Lat2_skip
	s_and_b64 vcc, exec, s[22:23]
	s_cbranch_vccnz .Lat2_nodma
	s_setprio 3
	s_mul_i32 s10, s28, 0xa000
	v_add_u32_e32 v198, s10, v218
	v_add_u32_e32 v199, s10, v219
	v_add_u32_e32 v200, s10, v209
	v_add_u32_e32 v201, s10, v208
	ds_read_b128 v[130:133], v198 offset:0
	ds_read_b128 v[134:137], v199 offset:0
	ds_read_b128 v[138:141], v200 offset:0
	ds_read_b128 v[142:145], v201 offset:0
	ds_read_b128 v[146:149], v198 offset:8192
	ds_read_b128 v[150:153], v199 offset:8192
	ds_read_b128 v[154:157], v200 offset:8192
	ds_read_b128 v[158:161], v201 offset:8192
	ds_read_b128 v[162:165], v198 offset:16384
	ds_read_b128 v[166:169], v199 offset:16384
	ds_read_b128 v[170:173], v200 offset:16384
	ds_read_b128 v[176:179], v201 offset:16384
	s_waitcnt lgkmcnt(8)
	v_mfma_f32_32x32x16_bf16 v[66:81], v[130:133], v[118:121], 0
	v_mfma_f32_32x32x16_bf16 v[66:81], v[134:137], v[114:117], v[66:81]
	v_mfma_f32_32x32x16_bf16 v[66:81], v[138:141], v[110:113], v[66:81]
	v_mfma_f32_32x32x16_bf16 v[66:81], v[142:145], v[106:109], v[66:81]
	ds_read_b128 v[130:133], v198 offset:4096
	ds_read_b128 v[134:137], v199 offset:4096
	ds_read_b128 v[138:141], v200 offset:4096
	ds_read_b128 v[142:145], v201 offset:4096
	s_waitcnt lgkmcnt(8)
	v_mfma_f32_32x32x16_bf16 v[66:81], v[146:149], v[102:105], v[66:81]
	v_mfma_f32_32x32x16_bf16 v[66:81], v[150:153], v[98:101], v[66:81]
	v_mfma_f32_32x32x16_bf16 v[66:81], v[154:157], v[94:97], v[66:81]
	v_mfma_f32_32x32x16_bf16 v[66:81], v[158:161], v[90:93], v[66:81]
	ds_read_b128 v[146:149], v198 offset:12288
	ds_read_b128 v[150:153], v199 offset:12288
	ds_read_b128 v[154:157], v200 offset:12288
	ds_read_b128 v[158:161], v201 offset:12288
	s_waitcnt lgkmcnt(8)
	v_mfma_f32_32x32x16_bf16 v[66:81], v[162:165], v[86:89], v[66:81]
	v_mfma_f32_32x32x16_bf16 v[66:81], v[166:169], v[126:129], v[66:81]
	v_mfma_f32_32x32x16_bf16 v[66:81], v[170:173], v[82:85], v[66:81]
	v_mfma_f32_32x32x16_bf16 v[66:81], v[176:179], v[122:125], v[66:81]
	s_setprio 2
	ds_read_b128 v[162:165], v198 offset:20480
	ds_read_b128 v[166:169], v199 offset:20480
	ds_read_b128 v[170:173], v200 offset:20480
	ds_read_b128 v[176:179], v201 offset:20480
	s_waitcnt lgkmcnt(8)
	v_mfma_f32_32x32x16_bf16 v[182:197], v[130:133], v[118:121], 0
	v_mfma_f32_32x32x16_bf16 v[182:197], v[134:137], v[114:117], v[182:197]
	v_mfma_f32_32x32x16_bf16 v[182:197], v[138:141], v[110:113], v[182:197]
	v_mfma_f32_32x32x16_bf16 v[182:197], v[142:145], v[106:109], v[182:197]
	ds_read_b128 v[130:133], v198 offset:24576
	ds_read_b128 v[134:137], v198 offset:28672
	ds_read_b128 v[138:141], v198 offset:32768
	ds_read_b128 v[142:145], v198 offset:36864
	s_waitcnt lgkmcnt(8)
	v_mfma_f32_32x32x16_bf16 v[182:197], v[146:149], v[102:105], v[182:197]
	v_med3_f32 v66, v66, s4, v236
	v_exp_f32_e32 v66, v66
	v_med3_f32 v67, v67, s4, v236
	v_exp_f32_e32 v67, v67
	v_mfma_f32_32x32x16_bf16 v[182:197], v[150:153], v[98:101], v[182:197]
	v_med3_f32 v68, v68, s4, v236
	v_exp_f32_e32 v68, v68
	v_med3_f32 v69, v69, s4, v236
	v_exp_f32_e32 v69, v69
	v_mfma_f32_32x32x16_bf16 v[182:197], v[154:157], v[94:97], v[182:197]
	v_med3_f32 v70, v70, s4, v236
	v_exp_f32_e32 v70, v70
	v_med3_f32 v71, v71, s4, v236
	v_exp_f32_e32 v71, v71
	v_mfma_f32_32x32x16_bf16 v[182:197], v[158:161], v[90:93], v[182:197]
	v_med3_f32 v72, v72, s4, v236
	v_exp_f32_e32 v72, v72
	v_med3_f32 v73, v73, s4, v236
	v_exp_f32_e32 v73, v73
	ds_read_b128 v[146:149], v199 offset:24576
	ds_read_b128 v[150:153], v199 offset:28672
	ds_read_b128 v[154:157], v199 offset:32768
	ds_read_b128 v[158:161], v199 offset:36864
	s_waitcnt lgkmcnt(8)
	v_mfma_f32_32x32x16_bf16 v[182:197], v[162:165], v[86:89], v[182:197]
	v_med3_f32 v74, v74, s4, v236
	v_exp_f32_e32 v74, v74
	v_med3_f32 v75, v75, s4, v236
	v_exp_f32_e32 v75, v75
	v_add_f32_e32 v202, v66, v67
	v_add_f32_e32 v202, v202, v68
	v_mfma_f32_32x32x16_bf16 v[182:197], v[166:169], v[126:129], v[182:197]
	v_med3_f32 v76, v76, s4, v236
	v_exp_f32_e32 v76, v76
	v_med3_f32 v77, v77, s4, v236
	v_exp_f32_e32 v77, v77
	v_add_f32_e32 v202, v202, v69
	v_add_f32_e32 v202, v202, v70
	v_mfma_f32_32x32x16_bf16 v[182:197], v[170:173], v[82:85], v[182:197]
	v_med3_f32 v78, v78, s4, v236
	v_exp_f32_e32 v78, v78
	v_med3_f32 v79, v79, s4, v236
	v_exp_f32_e32 v79, v79
	v_add_f32_e32 v202, v202, v71
	v_add_f32_e32 v202, v202, v72
	v_mfma_f32_32x32x16_bf16 v[182:197], v[176:179], v[122:125], v[182:197]
	v_med3_f32 v80, v80, s4, v236
	v_exp_f32_e32 v80, v80
	v_med3_f32 v81, v81, s4, v236
	v_exp_f32_e32 v81, v81
	v_add_f32_e32 v202, v202, v73
	s_setprio 1
	ds_read_b128 v[162:165], v200 offset:24576
	ds_read_b128 v[166:169], v200 offset:28672
	ds_read_b128 v[170:173], v200 offset:32768
	ds_read_b128 v[176:179], v200 offset:36864
	v_cvt_pk_bf16_f32 v66, v66, v67
	v_cvt_pk_bf16_f32 v67, v68, v69
	v_cvt_pk_bf16_f32 v68, v70, v71
	v_cvt_pk_bf16_f32 v69, v72, v73
	v_add_f32_e32 v202, v202, v74
	v_add_f32_e32 v202, v202, v75
	s_waitcnt lgkmcnt(8)
	v_mfma_f32_32x32x16_bf16 v[50:65], v[66:69], v[130:133], v[50:65]
	v_med3_f32 v182, v182, s4, v236
	v_exp_f32_e32 v182, v182
	v_med3_f32 v183, v183, s4, v236
	v_exp_f32_e32 v183, v183
	v_add_f32_e32 v202, v202, v76
	v_add_f32_e32 v202, v202, v77
	v_mfma_f32_32x32x16_bf16 v[34:49], v[66:69], v[134:137], v[34:49]
	v_med3_f32 v184, v184, s4, v236
	v_exp_f32_e32 v184, v184
	v_med3_f32 v185, v185, s4, v236
	v_exp_f32_e32 v185, v185
	v_add_f32_e32 v202, v202, v78
	v_add_f32_e32 v202, v202, v79
	v_mfma_f32_32x32x16_bf16 v[18:33], v[66:69], v[138:141], v[18:33]
	v_med3_f32 v186, v186, s4, v236
	v_exp_f32_e32 v186, v186
	v_med3_f32 v187, v187, s4, v236
	v_exp_f32_e32 v187, v187
	v_add_f32_e32 v202, v202, v80
	v_add_f32_e32 v202, v202, v81
	v_mfma_f32_32x32x16_bf16 v[2:17], v[66:69], v[142:145], v[2:17]
	v_med3_f32 v188, v188, s4, v236
	v_exp_f32_e32 v188, v188
	v_med3_f32 v189, v189, s4, v236
	v_exp_f32_e32 v189, v189
	v_cvt_pk_bf16_f32 v70, v74, v75
	v_cvt_pk_bf16_f32 v71, v76, v77
	v_cvt_pk_bf16_f32 v72, v78, v79
	v_cvt_pk_bf16_f32 v73, v80, v81
	ds_read_b128 v[130:133], v201 offset:24576
	ds_read_b128 v[134:137], v201 offset:28672
	ds_read_b128 v[138:141], v201 offset:32768
	ds_read_b128 v[142:145], v201 offset:36864
	s_waitcnt lgkmcnt(8)
	v_mfma_f32_32x32x16_bf16 v[50:65], v[70:73], v[146:149], v[50:65]
	v_med3_f32 v190, v190, s4, v236
	v_exp_f32_e32 v190, v190
	v_med3_f32 v191, v191, s4, v236
	v_exp_f32_e32 v191, v191
	v_add_f32_e32 v203, v182, v183
	v_add_f32_e32 v203, v203, v184
	v_mfma_f32_32x32x16_bf16 v[34:49], v[70:73], v[150:153], v[34:49]
	v_med3_f32 v192, v192, s4, v236
	v_exp_f32_e32 v192, v192
	v_med3_f32 v193, v193, s4, v236
	v_exp_f32_e32 v193, v193
	v_add_f32_e32 v203, v203, v185
	v_add_f32_e32 v203, v203, v186
	v_mfma_f32_32x32x16_bf16 v[18:33], v[70:73], v[154:157], v[18:33]
	v_med3_f32 v194, v194, s4, v236
	v_exp_f32_e32 v194, v194
	v_med3_f32 v195, v195, s4, v236
	v_exp_f32_e32 v195, v195
	v_add_f32_e32 v203, v203, v187
	v_mfma_f32_32x32x16_bf16 v[2:17], v[70:73], v[158:161], v[2:17]
	v_med3_f32 v196, v196, s4, v236
	v_exp_f32_e32 v196, v196
	v_med3_f32 v197, v197, s4, v236
	v_exp_f32_e32 v197, v197
	v_add_f32_e32 v203, v203, v188
	v_cvt_pk_bf16_f32 v182, v182, v183
	v_cvt_pk_bf16_f32 v183, v184, v185
	v_cvt_pk_bf16_f32 v184, v186, v187
	v_cvt_pk_bf16_f32 v185, v188, v189
	v_add_f32_e32 v203, v203, v189
	s_setprio 0
	s_waitcnt lgkmcnt(4)
	v_mfma_f32_32x32x16_bf16 v[50:65], v[182:185], v[162:165], v[50:65]
	v_mad_u64_u32 v[204:205], s[10:11], s86, v228, v[174:175]
	s_mul_i32 s10, s7, 0xa000
	s_add_i32 s10, s0, s10
	s_mov_b32 m0, s10
	v_lshl_add_u64 v[206:207], v[204:205], 0, s[94:95]
	global_load_lds_dwordx4 v[204:205], off
	v_add_f32_e32 v203, v203, v190
	v_add_f32_e32 v203, v203, v191
	v_add_f32_e32 v203, v203, v192
	v_mfma_f32_32x32x16_bf16 v[34:49], v[182:185], v[166:169], v[34:49]
	s_add_i32 m0, s10, 0x2000
	v_lshl_add_u64 v[204:205], v[204:205], 0, s[96:97]
	global_load_lds_dwordx4 v[206:207], off
	v_add_f32_e32 v203, v203, v193
	v_add_f32_e32 v203, v203, v194
	v_add_f32_e32 v203, v203, v195
	v_mfma_f32_32x32x16_bf16 v[18:33], v[182:185], v[170:173], v[18:33]
	s_add_i32 m0, s10, 0x4000
	s_nop 0
	global_load_lds_dwordx4 v[204:205], off
	v_lshl_add_u64 v[204:205], s[86:87], 1, v[180:181]
	s_add_i32 m0, s10, 0x6000
	v_add_f32_e32 v203, v203, v196
	v_add_f32_e32 v203, v203, v197
	v_cvt_pk_bf16_f32 v186, v190, v191
	v_cvt_pk_bf16_f32 v187, v192, v193
	v_cvt_pk_bf16_f32 v188, v194, v195
	v_cvt_pk_bf16_f32 v189, v196, v197
	v_mfma_f32_32x32x16_bf16 v[2:17], v[182:185], v[176:179], v[2:17]
	global_load_lds_dwordx4 v[204:205], off
	v_lshl_add_u64 v[204:205], v[204:205], 0, s[92:93]
	s_add_i32 m0, s10, 0x8000
	v_add_f32_e32 v202, v202, v203
	v_add_f32_e32 v0, v0, v202
	s_waitcnt lgkmcnt(0)
	v_mfma_f32_32x32x16_bf16 v[50:65], v[186:189], v[130:133], v[50:65]
	global_load_lds_dwordx4 v[204:205], off
	v_mfma_f32_32x32x16_bf16 v[34:49], v[186:189], v[134:137], v[34:49]
	v_mfma_f32_32x32x16_bf16 v[18:33], v[186:189], v[138:141], v[18:33]
	v_mfma_f32_32x32x16_bf16 v[2:17], v[186:189], v[142:145], v[2:17]
	s_waitcnt vmcnt(5) lgkmcnt(0)
	s_branch .LBB0_573
